# nt hint on the once-read loads of gla_o and of the rwkv_post loop
# baseline (speedup 1.0000x reference)
.LBB0_1100:
	v_lshl_add_u64 v[30:31], v[64:65], 0, v[60:61]
	v_add_co_u32_e64 v90, s[4:5], s21, v30
	v_lshl_add_u64 v[74:75], v[62:63], 0, v[60:61]
	s_nop 0
	v_addc_co_u32_e64 v91, s[4:5], 0, v31, s[4:5]
	v_add_co_u32_e64 v82, s[4:5], s22, v74
	v_and_b32_e32 v77, 0xfff, v56
	s_nop 0
	v_addc_co_u32_e64 v83, s[4:5], 0, v75, s[4:5]
	v_add_co_u32_e64 v74, s[4:5], s23, v74
	v_lshl_add_u64 v[72:73], v[66:67], 0, v[60:61]
	s_nop 0
	v_addc_co_u32_e64 v75, s[4:5], 0, v75, s[4:5]
	v_cmp_ne_u32_e64 s[0:1], 0, v77
	v_add_co_u32_e64 v86, s[4:5], s26, v72
	s_nop 0
	v_cndmask_b32_e64 v77, 0, 1, s[0:1]
	v_addc_co_u32_e64 v87, s[4:5], 0, v73, s[4:5]
	v_mov_b64_e32 v[38:39], s[44:45]
	v_add_co_u32_e32 v98, vcc, s20, v30
	global_load_dwordx4 v[78:81], v[90:91], off nt
	s_nop 0
	global_load_dwordx4 v[82:85], v[82:83], off offset:2048 nt
	s_nop 0
	global_load_dwordx4 v[86:89], v[86:87], off nt
	s_nop 0
	global_load_dwordx4 v[90:93], v[90:91], off offset:2048 nt
	s_nop 0
	global_load_dwordx4 v[94:97], v[74:75], off nt
	v_sub_co_u32_e64 v74, s[4:5], v56, v77
	v_cndmask_b32_e64 v30, 0, 1.0, s[0:1]
	v_addc_co_u32_e32 v99, vcc, 0, v31, vcc
	v_mad_u64_u32 v[38:39], s[0:1], v74, s11, v[38:39]
	v_subbrev_co_u32_e64 v75, s[4:5], 0, v57, s[4:5]
	v_add_co_u32_e32 v110, vcc, 0x100000, v72
	v_mov_b32_e32 v72, v39
	s_nop 0
	v_addc_co_u32_e32 v111, vcc, 0, v73, vcc
	v_mad_u64_u32 v[72:73], s[0:1], v75, s11, v[72:73]
	v_lshl_add_u64 v[56:57], v[56:57], 0, s[12:13]
	v_mov_b32_e32 v39, v72
	v_cmp_lt_i32_e32 vcc, s33, v56
	v_lshl_add_u64 v[38:39], v[38:39], 0, v[58:59]
	s_or_b64 s[8:9], vcc, s[8:9]
	v_add_co_u32_e32 v72, vcc, s10, v38
	global_load_dwordx4 v[98:101], v[98:99], off offset:2048 nt
	s_nop 0
	v_addc_co_u32_e32 v73, vcc, 0, v39, vcc
	v_add_co_u32_e32 v38, vcc, s3, v38
	v_lshl_add_u64 v[66:67], v[66:67], 0, s[18:19]
	s_nop 0
	v_addc_co_u32_e32 v39, vcc, 0, v39, vcc
	global_load_dwordx4 v[72:75], v[72:73], off offset:2048 nt
	s_nop 0
	global_load_dwordx4 v[102:105], v[38:39], off nt
	global_load_dwordx4 v[106:109], v[38:39], off offset:2048 nt
	v_lshl_add_u64 v[62:63], v[62:63], 0, s[14:15]
	v_lshl_add_u64 v[64:65], v[64:65], 0, s[16:17]
	s_waitcnt vmcnt(8)
	v_and_b32_e32 v39, 0xffff0000, v78
	s_waitcnt vmcnt(7)
	v_and_b32_e32 v113, 0xffff0000, v82
	s_waitcnt vmcnt(6)
	v_lshlrev_b32_e32 v114, 16, v86
	v_lshlrev_b32_e32 v112, 16, v82
	v_and_b32_e32 v82, 0xffff0000, v86
	v_add_f32_e32 v31, 0, v114
	v_lshlrev_b32_e32 v115, 16, v87
	v_add_f32_e32 v31, v31, v82
	v_lshlrev_b32_e32 v38, 16, v78
	v_and_b32_e32 v117, 0xffff0000, v79
	v_lshlrev_b32_e32 v116, 16, v79
	v_and_b32_e32 v79, 0xffff0000, v83
	v_lshlrev_b32_e32 v78, 16, v83
	v_and_b32_e32 v83, 0xffff0000, v87
	v_add_f32_e32 v31, v31, v115
	v_lshlrev_b32_e32 v120, 16, v88
	v_add_f32_e32 v31, v31, v83
	v_and_b32_e32 v119, 0xffff0000, v84
	v_lshlrev_b32_e32 v118, 16, v84
	v_and_b32_e32 v84, 0xffff0000, v88
	v_add_f32_e32 v31, v31, v120
	v_lshlrev_b32_e32 v121, 16, v89
	v_pk_add_f32 v[112:113], v[112:113], -1.0 op_sel_hi:[1,0]
	v_pk_add_f32 v[118:119], v[118:119], -1.0 op_sel_hi:[1,0]
	v_add_f32_e32 v31, v31, v84
	v_and_b32_e32 v87, 0xffff0000, v80
	v_lshlrev_b32_e32 v86, 16, v80
	v_and_b32_e32 v123, 0xffff0000, v81
	v_lshlrev_b32_e32 v122, 16, v81
	v_and_b32_e32 v81, 0xffff0000, v85
	v_lshlrev_b32_e32 v80, 16, v85
	v_and_b32_e32 v85, 0xffff0000, v89
	s_waitcnt vmcnt(3)
	v_and_b32_e32 v131, 0xffff0000, v98
	v_lshlrev_b32_e32 v130, 16, v98
	v_and_b32_e32 v133, 0xffff0000, v99
	v_lshlrev_b32_e32 v132, 16, v99
	v_and_b32_e32 v99, 0xffff0000, v100
	v_lshlrev_b32_e32 v98, 16, v100
	v_and_b32_e32 v135, 0xffff0000, v101
	v_lshlrev_b32_e32 v134, 16, v101
	v_pk_fma_f32 v[100:101], v[48:49], v[112:113], 1.0 op_sel_hi:[1,1,0]
	v_pk_fma_f32 v[112:113], v[40:41], v[118:119], 1.0 op_sel_hi:[1,1,0]
	s_waitcnt vmcnt(2)
	v_and_b32_e32 v119, 0xffff0000, v72
	v_lshlrev_b32_e32 v118, 16, v72
	s_waitcnt vmcnt(1)
	v_and_b32_e32 v137, 0xffff0000, v102
	v_lshlrev_b32_e32 v136, 16, v102
	v_add_f32_e32 v31, v31, v121
	v_and_b32_e32 v141, 0xffff0000, v73
	v_lshlrev_b32_e32 v140, 16, v73
	v_and_b32_e32 v73, 0xffff0000, v103
	v_lshlrev_b32_e32 v72, 16, v103
	v_and_b32_e32 v103, 0xffff0000, v74
	v_lshlrev_b32_e32 v102, 16, v74
	v_and_b32_e32 v143, 0xffff0000, v104
	v_lshlrev_b32_e32 v142, 16, v104
	v_and_b32_e32 v151, 0xffff0000, v75
	v_lshlrev_b32_e32 v150, 16, v75
	v_and_b32_e32 v75, 0xffff0000, v105
	v_lshlrev_b32_e32 v74, 16, v105
	v_pk_fma_f32 v[104:105], v[30:31], v[118:119], v[130:131] op_sel_hi:[0,1,1] neg_lo:[0,0,1] neg_hi:[0,0,1]
	v_pk_fma_f32 v[118:119], v[30:31], v[136:137], v[38:39] op_sel_hi:[0,1,1] neg_lo:[0,0,1] neg_hi:[0,0,1]
	v_add_f32_e32 v77, v31, v85
	v_pk_fma_f32 v[38:39], v[24:25], v[118:119], v[38:39]
	v_pk_add_f32 v[78:79], v[78:79], -1.0 op_sel_hi:[1,0]
	v_add_f32_dpp v77, v77, v77 quad_perm:[1,0,3,2] row_mask:0xf bank_mask:0xf bound_ctrl:1
	v_pk_add_f32 v[80:81], v[80:81], -1.0 op_sel_hi:[1,0]
	v_pk_fma_f32 v[72:73], v[30:31], v[72:73], v[116:117] op_sel_hi:[0,1,1] neg_lo:[0,0,1] neg_hi:[0,0,1]
	v_pk_fma_f32 v[74:75], v[30:31], v[74:75], v[122:123] op_sel_hi:[0,1,1] neg_lo:[0,0,1] neg_hi:[0,0,1]
	v_pk_fma_f32 v[104:105], v[8:9], v[104:105], v[130:131]
	v_pk_mul_f32 v[38:39], v[38:39], v[100:101]
	v_add_f32_dpp v77, v77, v77 quad_perm:[2,3,0,1] row_mask:0xf bank_mask:0xf bound_ctrl:1
	v_lshlrev_b32_e32 v89, 16, v91
	v_lshlrev_b32_e32 v88, 16, v90
	v_and_b32_e32 v91, 0xffff0000, v91
	v_and_b32_e32 v90, 0xffff0000, v90
	v_lshlrev_b32_e32 v127, 16, v93
	v_lshlrev_b32_e32 v126, 16, v92
	v_and_b32_e32 v93, 0xffff0000, v93
	v_and_b32_e32 v92, 0xffff0000, v92
	v_pk_fma_f32 v[78:79], v[50:51], v[78:79], 1.0 op_sel_hi:[1,1,0]
	v_pk_fma_f32 v[80:81], v[42:43], v[80:81], 1.0 op_sel_hi:[1,1,0]
	s_waitcnt vmcnt(0)
	v_lshlrev_b32_e32 v139, 16, v107
	v_lshlrev_b32_e32 v138, 16, v106
	v_and_b32_e32 v107, 0xffff0000, v107
	v_and_b32_e32 v106, 0xffff0000, v106
	v_lshlrev_b32_e32 v149, 16, v109
	v_lshlrev_b32_e32 v148, 16, v108
	v_and_b32_e32 v109, 0xffff0000, v109
	v_and_b32_e32 v108, 0xffff0000, v108
	v_pk_fma_f32 v[136:137], v[30:31], v[140:141], v[132:133] op_sel_hi:[0,1,1] neg_lo:[0,0,1] neg_hi:[0,0,1]
	v_pk_fma_f32 v[140:141], v[30:31], v[142:143], v[86:87] op_sel_hi:[0,1,1] neg_lo:[0,0,1] neg_hi:[0,0,1]
	v_pk_fma_f32 v[72:73], v[26:27], v[72:73], v[116:117]
	v_pk_fma_f32 v[74:75], v[34:35], v[74:75], v[122:123]
	v_pk_mul_f32 v[38:39], v[104:105], v[38:39]
	v_add_f32_dpp v77, v77, v77 row_half_mirror row_mask:0xf bank_mask:0xf bound_ctrl:1
	v_pk_fma_f32 v[102:103], v[30:31], v[102:103], v[98:99] op_sel_hi:[0,1,1] neg_lo:[0,0,1] neg_hi:[0,0,1]
	v_pk_fma_f32 v[142:143], v[30:31], v[150:151], v[134:135] op_sel_hi:[0,1,1] neg_lo:[0,0,1] neg_hi:[0,0,1]
	v_pk_fma_f32 v[138:139], v[30:31], v[138:139], v[88:89] op_sel_hi:[0,1,1] neg_lo:[0,0,1] neg_hi:[0,0,1]
	v_pk_fma_f32 v[106:107], v[30:31], v[106:107], v[90:91] op_sel_hi:[0,1,1] neg_lo:[0,0,1] neg_hi:[0,0,1]
	v_pk_fma_f32 v[148:149], v[30:31], v[148:149], v[126:127] op_sel_hi:[0,1,1] neg_lo:[0,0,1] neg_hi:[0,0,1]
	v_pk_fma_f32 v[30:31], v[30:31], v[108:109], v[92:93] op_sel_hi:[0,1,1] neg_lo:[0,0,1] neg_hi:[0,0,1]
	v_pk_fma_f32 v[108:109], v[10:11], v[136:137], v[132:133]
	v_pk_fma_f32 v[86:87], v[32:33], v[140:141], v[86:87]
	v_pk_mul_f32 v[72:73], v[72:73], v[78:79]
	v_pk_mul_f32 v[74:75], v[74:75], v[80:81]
	v_pk_mul_f32 v[38:39], v[52:53], v[38:39]
	v_mul_f32_e32 v80, 0x3c800000, v77
	v_pk_mul_f32 v[78:79], v[86:87], v[112:113]
	v_pk_mul_f32 v[72:73], v[108:109], v[72:73]
	v_add_f32_e32 v38, 0, v38
	v_pk_add_f32 v[86:87], v[114:115], v[80:81] op_sel_hi:[1,0] neg_lo:[0,1] neg_hi:[0,1]
	v_pk_add_f32 v[82:83], v[82:83], v[80:81] op_sel_hi:[1,0] neg_lo:[0,1] neg_hi:[0,1]
	v_pk_fma_f32 v[98:99], v[4:5], v[102:103], v[98:99]
	v_pk_mul_f32 v[72:73], v[54:55], v[72:73]
	v_add_f32_e32 v77, v39, v38
	v_mov_b32_e32 v38, v86
	v_mov_b32_e32 v39, v82
	v_pk_fma_f32 v[30:31], v[22:23], v[30:31], v[92:93]
	v_pk_mul_f32 v[78:79], v[98:99], v[78:79]
	v_pk_add_f32 v[92:93], v[120:121], v[80:81] op_sel_hi:[1,0] neg_lo:[0,1] neg_hi:[0,1]
	v_pk_add_f32 v[80:81], v[84:85], v[80:81] op_sel_hi:[1,0] neg_lo:[0,1] neg_hi:[0,1]
	v_mov_b32_e32 v84, v83
	v_mov_b32_e32 v85, v87
	v_add_f32_e32 v72, v72, v77
	v_pk_mul_f32 v[38:39], v[38:39], v[38:39]
	v_pk_fma_f32 v[102:103], v[6:7], v[142:143], v[134:135]
	v_pk_mul_f32 v[78:79], v[44:45], v[78:79]
	v_pk_mul_f32 v[84:85], v[84:85], v[84:85]
	v_add_f32_e32 v72, v73, v72
	v_add_f32_e32 v38, v38, v39
	v_pk_mul_f32 v[74:75], v[102:103], v[74:75]
	v_mov_b32_e32 v98, v80
	v_mov_b32_e32 v99, v92
	v_add_f32_e32 v39, v78, v72
	v_add_f32_e32 v38, v85, v38
	v_pk_mul_f32 v[74:75], v[46:47], v[74:75]
	v_pk_mul_f32 v[98:99], v[98:99], v[98:99]
	v_add_f32_e32 v39, v79, v39
	v_add_f32_e32 v38, v84, v38
	v_mov_b32_e32 v100, v81
	v_mov_b32_e32 v101, v93
	v_add_f32_e32 v39, v74, v39
	v_add_f32_e32 v38, v99, v38
	v_pk_mul_f32 v[100:101], v[100:101], v[100:101]
	v_add_f32_e32 v39, v75, v39
	v_add_f32_e32 v38, v98, v38
	v_add_f32_e32 v38, v101, v38
	v_add_f32_dpp v39, v39, v39 quad_perm:[1,0,3,2] row_mask:0xf bank_mask:0xf bound_ctrl:1
	v_add_f32_e32 v72, v100, v38
	v_pk_fma_f32 v[88:89], v[28:29], v[138:139], v[88:89]
	v_add_f32_dpp v39, v39, v39 quad_perm:[2,3,0,1] row_mask:0xf bank_mask:0xf bound_ctrl:1
	v_pk_fma_f32 v[90:91], v[18:19], v[106:107], v[90:91]
	v_pk_fma_f32 v[106:107], v[36:37], v[148:149], v[126:127]
	v_add_f32_dpp v38, v39, v39 row_half_mirror row_mask:0xf bank_mask:0xf bound_ctrl:1
	v_add_f32_dpp v39, v72, v72 quad_perm:[1,0,3,2] row_mask:0xf bank_mask:0xf bound_ctrl:1
	v_lshlrev_b32_e32 v125, 16, v95
	v_lshlrev_b32_e32 v124, 16, v94
	v_add_f32_dpp v39, v39, v39 quad_perm:[2,3,0,1] row_mask:0xf bank_mask:0xf bound_ctrl:1
	v_lshlrev_b32_e32 v129, 16, v97
	v_lshlrev_b32_e32 v128, 16, v96
	v_add_f32_dpp v39, v39, v39 row_half_mirror row_mask:0xf bank_mask:0xf bound_ctrl:1
	v_fmamk_f32 v39, v39, 0x3c800000, v76
	v_mul_f32_e32 v72, 0x4b800000, v39
	v_cmp_gt_f32_e32 vcc, s28, v39
	v_and_b32_e32 v95, 0xffff0000, v95
	v_and_b32_e32 v94, 0xffff0000, v94
	v_cndmask_b32_e32 v39, v39, v72, vcc
	v_rsq_f32_e32 v39, v39
	v_and_b32_e32 v97, 0xffff0000, v97
	v_and_b32_e32 v96, 0xffff0000, v96
	v_mul_f32_e32 v72, 0x45800000, v39
	v_cndmask_b32_e32 v72, v39, v72, vcc
	v_pk_mul_f32 v[74:75], v[86:87], v[72:73] op_sel_hi:[1,0]
	v_pk_mul_f32 v[78:79], v[82:83], v[72:73] op_sel_hi:[1,0]
	v_pk_mul_f32 v[82:83], v[92:93], v[72:73] op_sel_hi:[1,0]
	v_pk_mul_f32 v[72:73], v[80:81], v[72:73] op_sel_hi:[1,0]
	v_pk_fma_f32 v[74:75], v[12:13], v[74:75], v[0:1]
	v_pk_fma_f32 v[80:81], v[20:21], v[82:83], v[16:17]
	v_pk_fma_f32 v[78:79], v[70:71], v[78:79], v[68:69]
	v_pk_fma_f32 v[72:73], v[14:15], v[72:73], v[2:3]
	v_pk_fma_f32 v[74:75], v[88:89], v[38:39], v[74:75] op_sel_hi:[1,0,1]
	v_pk_fma_f32 v[80:81], v[106:107], v[38:39], v[80:81] op_sel_hi:[1,0,1]
	v_pk_fma_f32 v[78:79], v[90:91], v[38:39], v[78:79] op_sel_hi:[1,0,1]
	v_pk_fma_f32 v[30:31], v[30:31], v[38:39], v[72:73] op_sel_hi:[1,0,1]
	v_pk_mul_f32 v[38:39], v[74:75], v[124:125]
	v_pk_mul_f32 v[74:75], v[80:81], v[128:129]
	v_pk_mul_f32 v[72:73], v[78:79], v[94:95]
	v_pk_mul_f32 v[30:31], v[30:31], v[96:97]
	v_bfe_u32 v81, v38, 16, 1
	v_bfe_u32 v82, v39, 16, 1
	v_bfe_u32 v83, v74, 16, 1
	v_bfe_u32 v84, v75, 16, 1
	v_bfe_u32 v77, v31, 16, 1
	v_bfe_u32 v78, v30, 16, 1
	v_bfe_u32 v79, v73, 16, 1
	v_bfe_u32 v80, v72, 16, 1
	v_add3_u32 v75, v75, v84, s29
	v_add3_u32 v74, v74, v83, s29
	v_add3_u32 v39, v39, v82, s29
	v_add3_u32 v38, v38, v81, s29
	v_add3_u32 v72, v72, v80, s29
	v_add3_u32 v73, v73, v79, s29
	v_add3_u32 v30, v30, v78, s29
	v_add3_u32 v31, v31, v77, s29
	v_lshrrev_b32_e32 v38, 16, v38
	v_lshrrev_b32_e32 v39, 16, v39
	v_lshrrev_b32_e32 v74, 16, v74
	v_lshrrev_b32_e32 v75, 16, v75
	v_and_or_b32 v75, v31, s27, v75
	v_and_or_b32 v74, v30, s27, v74
	v_and_or_b32 v73, v73, s27, v39
	v_and_or_b32 v72, v72, s27, v38
	global_store_dwordx4 v[110:111], v[72:75], off
	s_andn2_b64 exec, exec, s[8:9]
	s_cbranch_execnz .LBB0_1100
